# v80 (LN peepholes) + windowed attention second score accumulator takes the -max vector as MFMA C operand directly (8 v_mov_b64 per tile removed), no interior-tile branch
# speedup vs baseline: 1.0016x; 1.0016x over previous
; #define MFMA32(a, b, c) __builtin_amdgcn_mfma_f32_32x32x16_bf16((a), (b), (c), 0, 0, 0)
; template <int MODE>
; DI void attn_item(const Params& p, int layer, int b, int hq, int qb, u16* lds, const int WAVE_S) {
;     ...
;     f32x16 sc[2];
; #pragma unroll
;     for (int k2 = 0; k2 < 2; ++k2) {
; #pragma unroll
;       for (int ks = 0; ks < 4; ++ks) {
;         const bf16x8 kf = *(const bf16x8*)(Ks + (k2 * 32 + r) * LSTR + ks * 16 + h * 8);
;         sc[k2] = (ks == 0) ? MFMA32(kf, qf[0], negm) : MFMA32(kf, qf[ks], sc[k2]);
;       }
;     }
;     if (MODE == 1) {
;       const float tposf = (float)(q0 + r - (kbase0 + t * 64) - 4 * h);
; #pragma unroll
;       for (int k2 = 0; k2 < 2; ++k2)
; #pragma unroll
;         for (int i = 0; i < 16; ++i) {
;           const float dist = fabsf(tposf - (float)(k2 * 32 + (i & 3) + 8 * (i >> 2)));
;           sc[k2][i] = (dist <= 128.f) ? (sc[k2][i] - slope2 * dist) : -1e30f;
;         }
;     }
.LBB0_184:
	v_max_i32_e32 v50, s85, v116
	v_add_u32_e32 v50, s96, v50
	v_cmp_gt_i32_e32 vcc, s34, v130
	s_and_saveexec_b64 s[18:19], vcc
	s_lshl_b32 s44, s28, 6
	s_add_i32 s44, s44, s84
	v_sub_u32_e32 v50, s44, v130
	s_or_b64 exec, exec, s[18:19]
	s_movk_i32 s18, 0x81
	v_cmp_gt_i32_e32 vcc, s18, v50
	s_and_saveexec_b64 s[44:45], vcc
	s_cbranch_execz .LBB0_180
	s_and_b32 s18, s97, 0x80
	s_mulk_i32 s18, 0x90
	v_add_u32_e32 v133, s18, v131
	ds_read_b128 v[50:53], v133
	ds_read_b128 v[54:57], v133 offset:32
	ds_read_b128 v[134:137], v133 offset:4608
	v_cvt_f32_i32_e32 v128, v132
	s_waitcnt lgkmcnt(2)
	v_mfma_f32_32x32x16_bf16 v[66:81], v[50:53], v[82:85], v[2:17]
	ds_read_b128 v[50:53], v133 offset:64
	s_waitcnt lgkmcnt(2)
	v_mfma_f32_32x32x16_bf16 v[66:81], v[54:57], v[86:89], v[66:81]
	s_waitcnt lgkmcnt(0)
	v_mfma_f32_32x32x16_bf16 v[66:81], v[50:53], v[90:93], v[66:81]
	ds_read_b128 v[50:53], v133 offset:96
	s_waitcnt lgkmcnt(0)
	v_mfma_f32_32x32x16_bf16 v[66:81], v[50:53], v[94:97], v[66:81]
	v_mfma_f32_32x32x16_bf16 v[50:65], v[134:137], v[82:85], v[2:17]
	ds_read_b128 v[134:137], v133 offset:4640
	s_waitcnt lgkmcnt(0)
	v_mfma_f32_32x32x16_bf16 v[50:65], v[134:137], v[86:89], v[50:65]
	ds_read_b128 v[134:137], v133 offset:4672
	s_waitcnt lgkmcnt(0)
	v_mfma_f32_32x32x16_bf16 v[50:65], v[134:137], v[90:93], v[50:65]
	ds_read_b128 v[134:137], v133 offset:4704
	s_waitcnt lgkmcnt(0)
	v_mfma_f32_32x32x16_bf16 v[50:65], v[134:137], v[94:97], v[50:65]
	v_add_f32_e32 v136, -1.0, v128
	s_nop 0
	s_nop 0
	v_fma_f32 v134, -v120, |v128|, v66
	v_fma_f32 v135, -v121, |v136|, v67
	v_cmp_le_f32_e64 vcc, |v136|, s89
	s_nop 1
	v_cndmask_b32_e32 v66, v146, v135, vcc
	v_cmp_le_f32_e64 vcc, |v128|, s89
	s_nop 1
	v_cndmask_b32_e32 v67, v146, v134, vcc
	v_pk_add_f32 v[134:135], v[128:129], s[2:3] op_sel_hi:[0,1]
	s_nop 0
	s_nop 0
	v_fma_f32 v136, -v120, |v134|, v68
	v_fma_f32 v137, -v121, |v135|, v69
	v_cmp_le_f32_e64 vcc, |v135|, s89
	s_nop 1
	v_cndmask_b32_e32 v68, v146, v137, vcc
	v_cmp_le_f32_e64 vcc, |v134|, s89
	v_pk_add_f32 v[134:135], v[128:129], s[38:39] op_sel_hi:[0,1]
	s_nop 0
	v_cndmask_b32_e32 v69, v146, v136, vcc
	s_nop 0
	v_fma_f32 v136, -v120, |v134|, v70
	v_fma_f32 v137, -v121, |v135|, v71
	v_cmp_le_f32_e64 vcc, |v135|, s89
	s_nop 1
	v_cndmask_b32_e32 v70, v146, v137, vcc
	v_cmp_le_f32_e64 vcc, |v134|, s89
	v_pk_add_f32 v[134:135], v[128:129], s[4:5] op_sel_hi:[0,1]
	s_nop 0
	v_cndmask_b32_e32 v71, v146, v136, vcc
	s_nop 0
	v_fma_f32 v136, -v120, |v134|, v72
	v_fma_f32 v137, -v121, |v135|, v73
	v_cmp_le_f32_e64 vcc, |v135|, s89
	s_nop 1
	v_cndmask_b32_e32 v72, v146, v137, vcc
	v_cmp_le_f32_e64 vcc, |v134|, s89
	v_pk_add_f32 v[134:135], v[128:129], s[52:53] op_sel_hi:[0,1]
	s_nop 0
	v_cndmask_b32_e32 v73, v146, v136, vcc
	s_nop 0
	v_fma_f32 v136, -v120, |v134|, v74
	v_fma_f32 v137, -v121, |v135|, v75
	v_cmp_le_f32_e64 vcc, |v135|, s89
	s_nop 1
	v_cndmask_b32_e32 v74, v146, v137, vcc
	v_cmp_le_f32_e64 vcc, |v134|, s89
	v_pk_add_f32 v[134:135], v[128:129], s[26:27] op_sel_hi:[0,1]
	s_nop 0
	v_cndmask_b32_e32 v75, v146, v136, vcc
	s_nop 0
	v_fma_f32 v136, -v120, |v134|, v76
	v_fma_f32 v137, -v121, |v135|, v77
	v_cmp_le_f32_e64 vcc, |v135|, s89
	s_nop 1
	v_cndmask_b32_e32 v76, v146, v137, vcc
	v_cmp_le_f32_e64 vcc, |v134|, s89
	v_pk_add_f32 v[134:135], v[128:129], s[76:77] op_sel_hi:[0,1]
	s_nop 0
	v_cndmask_b32_e32 v77, v146, v136, vcc
	s_nop 0
	v_fma_f32 v136, -v120, |v134|, v78
	v_fma_f32 v137, -v121, |v135|, v79
	v_cmp_le_f32_e64 vcc, |v135|, s89
	s_nop 1
	v_cndmask_b32_e32 v78, v146, v137, vcc
	v_cmp_le_f32_e64 vcc, |v134|, s89
	v_pk_add_f32 v[134:135], v[128:129], s[22:23] op_sel_hi:[0,1]
	s_nop 0
	v_cndmask_b32_e32 v79, v146, v136, vcc
	s_nop 0
	v_fma_f32 v136, -v120, |v134|, v80
	v_fma_f32 v137, -v121, |v135|, v81
	v_cmp_le_f32_e64 vcc, |v135|, s89
	s_nop 1
	v_cndmask_b32_e32 v80, v146, v137, vcc
	v_cmp_le_f32_e64 vcc, |v134|, s89
	v_pk_add_f32 v[134:135], v[128:129], s[10:11] op_sel_hi:[0,1]
	s_nop 0
	v_cndmask_b32_e32 v81, v146, v136, vcc
	s_nop 0
	v_fma_f32 v136, -v120, |v134|, v50
	v_fma_f32 v137, -v121, |v135|, v51
	v_cmp_le_f32_e64 vcc, |v135|, s89
	s_nop 1
	v_cndmask_b32_e32 v50, v146, v137, vcc
	v_cmp_le_f32_e64 vcc, |v134|, s89
	v_pk_add_f32 v[134:135], v[128:129], s[30:31] op_sel_hi:[0,1]
	s_nop 0
	v_cndmask_b32_e32 v51, v146, v136, vcc
	s_nop 0
	v_fma_f32 v136, -v120, |v134|, v52
	v_fma_f32 v137, -v121, |v135|, v53
	v_cmp_le_f32_e64 vcc, |v135|, s89
	s_nop 1
	v_cndmask_b32_e32 v52, v146, v137, vcc
	v_cmp_le_f32_e64 vcc, |v134|, s89
	v_pk_add_f32 v[134:135], v[128:129], s[20:21] op_sel_hi:[0,1]
	s_nop 0
	v_cndmask_b32_e32 v53, v146, v136, vcc
	s_nop 0
	v_fma_f32 v136, -v120, |v134|, v54
	v_fma_f32 v137, -v121, |v135|, v55
	v_cmp_le_f32_e64 vcc, |v135|, s89
	s_nop 1
; template <int MODE>
; DI void attn_item(const Params& p, int layer, int b, int hq, int qb, u16* lds, const int WAVE_S) {
;     ...
;     if (MODE == 1) {
;       const float tposf = (float)(q0 + r - (kbase0 + t * 64) - 4 * h);
; #pragma unroll
;       for (int k2 = 0; k2 < 2; ++k2)
; #pragma unroll
;         for (int i = 0; i < 16; ++i) {
;           const float dist = fabsf(tposf - (float)(k2 * 32 + (i & 3) + 8 * (i >> 2)));
;           sc[k2][i] = (dist <= 128.f) ? (sc[k2][i] - slope2 * dist) : -1e30f;
;         }
;     }
;     float mx0 = fmaxf(fmaxf(sc[0][0], sc[0][1]), sc[0][2]), mx1 = fmaxf(fmaxf(sc[1][0], sc[1][1]), sc[1][2]);
; #pragma unroll
;     for (int i = 3; i < 15; i += 2) { mx0 = fmaxf(fmaxf(mx0, sc[0][i]), sc[0][i + 1]); mx1 = fmaxf(fmaxf(mx1, sc[1][i]), sc[1][i + 1]); }
;     float mx = fmaxf(fmaxf(mx0, mx1), fmaxf(sc[0][15], sc[1][15]));
;     {
;       auto rr = __builtin_amdgcn_permlane32_swap(__float_as_uint(mx), __float_as_uint(mx), false, false);
;       mx = fmaxf(__uint_as_float(rr[0]), __uint_as_float(rr[1]));
;     }
;     if (__any(mx > 8.0f)) {
;       const float delta = fmaxf(mx, 0.f);
;       const float al = __builtin_amdgcn_exp2f(-delta);
; #pragma unroll
;       for (int k2 = 0; k2 < 2; ++k2)
; #pragma unroll
;         for (int i = 0; i < 16; ++i) sc[k2][i] -= delta;
; #pragma unroll
;       for (int dt = 0; dt < 2; ++dt)
; #pragma unroll
;         for (int i = 0; i < 16; ++i) o[dt][i] *= al;
;       l_run *= al;
;       m_run += delta;
; #pragma unroll
;       for (int i = 0; i < 16; ++i) negm[i] = -m_run;
;     }
	v_cndmask_b32_e32 v54, v146, v137, vcc
	v_cmp_le_f32_e64 vcc, |v134|, s89
	v_pk_add_f32 v[134:135], v[128:129], s[6:7] op_sel_hi:[0,1]
	s_nop 0
	v_cndmask_b32_e32 v55, v146, v136, vcc
	s_nop 0
	v_fma_f32 v136, -v120, |v134|, v56
	v_fma_f32 v137, -v121, |v135|, v57
	v_cmp_le_f32_e64 vcc, |v135|, s89
	s_nop 1
	v_cndmask_b32_e32 v56, v146, v137, vcc
	v_cmp_le_f32_e64 vcc, |v134|, s89
	v_pk_add_f32 v[134:135], v[128:129], s[42:43] op_sel_hi:[0,1]
	s_nop 0
	v_cndmask_b32_e32 v57, v146, v136, vcc
	s_nop 0
	v_fma_f32 v136, -v120, |v134|, v58
	v_fma_f32 v137, -v121, |v135|, v59
	v_cmp_le_f32_e64 vcc, |v135|, s89
	s_nop 1
	v_cndmask_b32_e32 v58, v146, v137, vcc
	v_cmp_le_f32_e64 vcc, |v134|, s89
	v_pk_add_f32 v[134:135], v[128:129], s[14:15] op_sel_hi:[0,1]
	s_nop 0
	v_cndmask_b32_e32 v59, v146, v136, vcc
	s_nop 0
	v_fma_f32 v136, -v120, |v134|, v60
	v_fma_f32 v137, -v121, |v135|, v61
	v_cmp_le_f32_e64 vcc, |v135|, s89
	s_nop 1
	v_cndmask_b32_e32 v60, v146, v137, vcc
	v_cmp_le_f32_e64 vcc, |v134|, s89
	v_pk_add_f32 v[134:135], v[128:129], s[82:83] op_sel_hi:[0,1]
	s_nop 0
	v_cndmask_b32_e32 v61, v146, v136, vcc
	s_nop 0
	v_fma_f32 v136, -v120, |v134|, v62
	v_fma_f32 v137, -v121, |v135|, v63
	v_cmp_le_f32_e64 vcc, |v135|, s89
	s_nop 1
	v_cndmask_b32_e32 v62, v146, v137, vcc
	v_cmp_le_f32_e64 vcc, |v134|, s89
	v_pk_add_f32 v[134:135], v[128:129], s[8:9] op_sel_hi:[0,1]
	s_nop 0
	v_cndmask_b32_e32 v63, v146, v136, vcc
	s_nop 0
	v_fma_f32 v136, -v120, |v134|, v64
	v_fma_f32 v137, -v121, |v135|, v65
	v_cmp_le_f32_e64 vcc, |v135|, s89
	v_max3_f32 v128, v67, v66, v69
	v_max3_f32 v128, v128, v68, v71
	v_cndmask_b32_e32 v64, v146, v137, vcc
	v_cmp_le_f32_e64 vcc, |v134|, s89
	v_max3_f32 v134, v51, v50, v53
	v_max3_f32 v134, v134, v52, v55
	v_max3_f32 v128, v128, v70, v73
	v_max3_f32 v134, v134, v54, v57
	v_max3_f32 v128, v128, v72, v75
	v_max3_f32 v134, v134, v56, v59
	v_max3_f32 v128, v128, v74, v77
	v_max3_f32 v134, v134, v58, v61
	v_cndmask_b32_e32 v65, v146, v136, vcc
	v_max3_f32 v128, v128, v76, v79
	v_max3_f32 v134, v134, v60, v63
	v_max3_f32 v128, v128, v78, v81
	v_max3_f32 v134, v134, v62, v65
	v_max_f32_e32 v135, v80, v64
	v_max3_f32 v128, v128, v134, v135
	v_mov_b32_e32 v134, v128
	s_nop 1
	v_permlane32_swap_b32_e32 v128, v134
	v_max_f32_e32 v134, v134, v134
	v_max_f32_e32 v128, v128, v128
	v_max_f32_e32 v128, v128, v134
	v_cmp_lt_f32_e32 vcc, s90, v128
	s_cbranch_vccz .LBB0_179
	v_max_f32_e32 v2, v128, v128
	v_max_f32_e32 v2, 0, v2
	v_exp_f32_e64 v4, -v2
	v_add_f32_e32 v115, v115, v2
	v_sub_f32_e32 v67, v67, v2
	v_sub_f32_e32 v66, v66, v2
	v_sub_f32_e32 v69, v69, v2
	v_sub_f32_e32 v68, v68, v2
	v_sub_f32_e32 v71, v71, v2
	v_sub_f32_e32 v70, v70, v2
	v_sub_f32_e32 v73, v73, v2
	v_sub_f32_e32 v72, v72, v2
	v_sub_f32_e32 v75, v75, v2
	v_sub_f32_e32 v74, v74, v2
	v_sub_f32_e32 v77, v77, v2
	v_sub_f32_e32 v76, v76, v2
	v_sub_f32_e32 v79, v79, v2
	v_sub_f32_e32 v78, v78, v2
	v_sub_f32_e32 v81, v81, v2
	v_sub_f32_e32 v80, v80, v2
	v_sub_f32_e32 v51, v51, v2
	v_sub_f32_e32 v50, v50, v2
	v_sub_f32_e32 v53, v53, v2
	v_sub_f32_e32 v52, v52, v2
	v_sub_f32_e32 v55, v55, v2
	v_sub_f32_e32 v54, v54, v2
	v_sub_f32_e32 v57, v57, v2
	v_sub_f32_e32 v56, v56, v2
	v_sub_f32_e32 v59, v59, v2
	v_sub_f32_e32 v58, v58, v2
	v_sub_f32_e32 v61, v61, v2
	v_sub_f32_e32 v60, v60, v2
	v_sub_f32_e32 v63, v63, v2
	v_sub_f32_e32 v62, v62, v2
	v_sub_f32_e32 v65, v65, v2
	v_sub_f32_e32 v64, v64, v2
	v_xor_b32_e32 v2, 0x80000000, v115
	v_pk_mul_f32 v[32:33], v[32:33], v[4:5] op_sel_hi:[1,0]
	v_pk_mul_f32 v[30:31], v[30:31], v[4:5] op_sel_hi:[1,0]
	v_pk_mul_f32 v[28:29], v[28:29], v[4:5] op_sel_hi:[1,0]
	v_pk_mul_f32 v[26:27], v[26:27], v[4:5] op_sel_hi:[1,0]
	v_pk_mul_f32 v[24:25], v[24:25], v[4:5] op_sel_hi:[1,0]
	v_pk_mul_f32 v[22:23], v[22:23], v[4:5] op_sel_hi:[1,0]
	v_pk_mul_f32 v[20:21], v[20:21], v[4:5] op_sel_hi:[1,0]
	v_pk_mul_f32 v[18:19], v[18:19], v[4:5] op_sel_hi:[1,0]
	v_pk_mul_f32 v[48:49], v[48:49], v[4:5] op_sel_hi:[1,0]
	v_pk_mul_f32 v[46:47], v[46:47], v[4:5] op_sel_hi:[1,0]
	v_pk_mul_f32 v[44:45], v[44:45], v[4:5] op_sel_hi:[1,0]
	v_pk_mul_f32 v[42:43], v[42:43], v[4:5] op_sel_hi:[1,0]
	v_pk_mul_f32 v[40:41], v[40:41], v[4:5] op_sel_hi:[1,0]
	v_pk_mul_f32 v[38:39], v[38:39], v[4:5] op_sel_hi:[1,0]
	v_pk_mul_f32 v[36:37], v[36:37], v[4:5] op_sel_hi:[1,0]
	v_pk_mul_f32 v[34:35], v[34:35], v[4:5] op_sel_hi:[1,0]
	v_mul_f32_e32 v129, v129, v4
	v_mov_b32_e32 v3, v2
	v_mov_b32_e32 v4, v2
	v_mov_b32_e32 v5, v2
	v_mov_b32_e32 v6, v2
	v_mov_b32_e32 v7, v2
	v_mov_b32_e32 v8, v2
	v_mov_b32_e32 v9, v2
	v_mov_b32_e32 v10, v2
	v_mov_b32_e32 v11, v2
	v_mov_b32_e32 v12, v2
	v_mov_b32_e32 v13, v2
	v_mov_b32_e32 v14, v2
	v_mov_b32_e32 v15, v2
	v_mov_b32_e32 v16, v2
	v_mov_b32_e32 v17, v2
	s_branch .LBB0_179
